# own-XCD work queues when the launch census shows all eight XCC ids populated (else original stealing), decided once per launch; grid-barrier non-leader acquire invalidate issued before polling
# speedup vs baseline: 1.0011x; 1.0011x over previous
; #define LAS __attribute__((address_space(3)))
; __device__ __forceinline__ unsigned xb_add(unsigned* p, unsigned v) { return __hip_atomic_fetch_add(p, v, __ATOMIC_RELAXED, __HIP_MEMORY_SCOPE_AGENT); }
; __device__ __forceinline__ unsigned xb_xcc_id() { return (unsigned)__builtin_amdgcn_s_getreg((3 << 11) | 20) & 0xFu; }
; __device__ __forceinline__ int karg32(int off) { return *(volatile CAS int*)((CAS char*)__builtin_amdgcn_kernarg_segment_ptr() + off); }
; #define ARG_WS() ((unsigned char*)karg64(8 * 19))
; __device__ __forceinline__ XcdBarrier xcd_barrier_post(unsigned* bar, volatile LAS unsigned* st) {
;     XcdBarrier b; b.bar = bar; b.x = xb_xcc_id(); b.st = st;
;     if (threadIdx.x == 0) (void)xb_add(&bar[XB_XCNT(b.x)], 1u);
;     return b;
; }
; template <int PHM, int ATTM> __global__ void __launch_bounds__(NWAVES * 64, 2) fwd_kernel(Args args) {
;     extern __shared__ __attribute__((aligned(16))) unsigned char lds_raw[];
;     LAS unsigned char* lds = (LAS unsigned char*)lds_raw;
;     for (int u = threadIdx.x; u < (LDS_BYTES - LDSCTL_OFF) / 4; u += NWAVES * 64) ((LAS unsigned*)(lds + LDSCTL_OFF))[u] = 0u;
;     __syncthreads();
;     XcdBarrier bar; bar.bar = nullptr; bar.x = 0; bar.st = nullptr;
;     if (N_LAUNCH_MODE == 0) bar = xcd_barrier_post((unsigned*)(ARG_WS() + WS_CTL) + CW_BAR, (volatile LAS unsigned*)(lds + MISC_OFF) + 8);
;     const int lo = karg32(8 * 20), hi = karg32(8 * 20 + 4);
_Z10fwd_kernelILi65535ELi15EEv4Args:
	s_mov_b32 s100, 0
	v_lshl_add_u32 v1, v0, 2, 0
	v_add_u32_e32 v1, 0x20000, v1
	v_mov_b32_e32 v2, 0
	s_mov_b32 s66, s2
	ds_write2st64_b32 v1, v2, v2 offset1:8
	ds_write2st64_b32 v1, v2, v2 offset0:16 offset1:24
	v_or_b32_e32 v1, 0x800, v0
	s_mov_b64 s[2:3], -1
	s_and_saveexec_b64 s[4:5], s[2:3]
	v_lshl_add_u32 v3, v1, 2, 0
	v_add_u32_e32 v3, 0x20000, v3
	ds_write_b32 v3, v2
	s_or_b64 exec, exec, s[4:5]
	s_and_saveexec_b64 s[4:5], s[2:3]
	s_add_i32 s2, 0, 0x20000
	v_lshl_add_u32 v1, v1, 2, s2
	v_mov_b32_e32 v2, 0
	ds_write_b32 v1, v2 offset:2048
	s_or_b64 exec, exec, s[4:5]
	v_or_b32_e32 v1, 0xc00, v0
	v_cmp_gt_u32_e64 s[2:3], 7, 6
	v_cmp_gt_u32_e64 s[6:7], 7, 5
	s_and_saveexec_b64 s[4:5], s[6:7]
	v_lshl_add_u32 v2, v1, 2, 0
	v_add_u32_e32 v2, 0x20000, v2
	v_mov_b32_e32 v3, 0
	ds_write_b32 v2, v3
	s_or_b64 exec, exec, s[4:5]
	s_and_saveexec_b64 s[4:5], s[2:3]
	s_add_i32 s2, 0, 0x20000
	v_lshl_add_u32 v1, v1, 2, s2
	v_mov_b32_e32 v2, 0
	ds_write_b32 v1, v2 offset:2048
	s_or_b64 exec, exec, s[4:5]
	s_waitcnt lgkmcnt(0)
	s_barrier
	s_load_dwordx2 s[2:3], s[0:1], 0x98
	s_getreg_b32 s4, hwreg(HW_REG_XCC_ID, 0, 4)
	v_cmp_eq_u32_e64 s[70:71], 0, v0
	s_waitcnt lgkmcnt(0)
	s_add_u32 s33, s2, 0x4000
	s_addc_u32 s38, s3, 0
	s_and_b32 s39, s4, 15
	s_and_saveexec_b64 s[4:5], s[70:71]
	s_cbranch_execz .LBB0_10
	s_lshl_b32 s6, s39, 8
	s_add_u32 s6, s33, s6
	s_addc_u32 s7, s38, 0
	v_mov_b32_e32 v1, 1
	v_mov_b64_e32 v[2:3], s[6:7]
	flat_atomic_add v[2:3], v1 offset:1024

; #define LAS __attribute__((address_space(3)))
; __device__ __forceinline__ unsigned xb_xcc_id() { return (unsigned)__builtin_amdgcn_s_getreg((3 << 11) | 20) & 0xFu; }
; #define WG_DRAW(cls, q) LAS int* slot = (LAS int*)(lds + MISC_OFF + 64); \
;         if (threadIdx.x == 0) *slot = (int)__hip_atomic_fetch_add(XQ_HEAD(cls, q), 1u, RLX_AGENT); \
;         __syncthreads(); const int it = *slot; __syncthreads();
; template <int ATTM> __device__ __forceinline__ void attention_phase(int layer, int lane, int rep, LAS unsigned char* lds, int wave) {
;     asm volatile("" : "+s"(wave));
;     ...
;     if ((ATTM & 2) && PK(2)) {
; #pragma unroll 1
;         for (int qq = 0; qq < 8; ++qq) { const int q = ((int)(xb_xcc_id() & 7u) + qq) & 7;
;             for (;;) { WG_DRAW(0, q); if (it >= 32) break;
.LBB0_544:
	s_cmp_lg_u32 s100, 0
	s_cbranch_scc1 .Lmy_xc_known
	s_load_dwordx2 s[12:13], s[0:1], 0x98
	v_and_b32_e32 v5, 7, v239
	v_lshlrev_b32_e32 v5, 8, v5
	v_add_u32_e32 v5, 0x4400, v5
	s_waitcnt lgkmcnt(0)
	global_load_dword v6, v5, s[12:13] sc1
	s_waitcnt vmcnt(0)
	v_cmp_ne_u32_e32 vcc, 0, v6
	s_nop 1
	s_and_b32 s100, vcc_lo, 0xff
	s_cmp_eq_u32 s100, 0xff
	s_cselect_b32 s100, 1, 8
